# mixA unit: the 8 mixing-matrix row loads and 3 gain-load pairs were each load+vmcnt(0) serialized; issued up front into free VGPRs with counted vmcnt (on comb9)
# speedup vs baseline: 1.0042x; 1.0042x over previous
; __device__ __forceinline__ unsigned cvt_pk_bf16(float lo, float hi) { unsigned r; asm volatile("v_cvt_pk_bf16_f32 %0, %1, %2" : "=v"(r) : "v"(lo), "v"(hi)); return r; }
; #define LAS __attribute__((address_space(3)))
;     template <class T> __device__ __forceinline__ T* w(size_t off) const { return (T*)(pp->ws + off); }
; __device__ __forceinline__ void mixA_unit(const Ctx& c, int l, int a) {
;     ...
;         const int s4 = (c.tid & 31) * 4;
;         const float* wsrc = c.f(I_AWS) + (size_t)(l * 8 + hh) * 128 * 128;
; #pragma unroll
;         for (int i = 0; i < 8; ++i) {
;             const int t = (c.tid >> 5) + 16 * i;
;             f32x4 w = *(const f32x4*)(wsrc + t * 128 + s4);
; #pragma unroll
;             for (int e = 0; e < 4; ++e) if (s4 + e > t) w[e] = 0.f;
;             *(LAS u32x2*)(WmB + t * 288 + s4 * 2) = (u32x2){pg8::cvt_pk_bf16(w[0], w[1]), pg8::cvt_pk_bf16(w[2], w[3])};
;         }
;     }
;     __syncthreads();
.LBB0_1076:
	s_or_b64 exec, exec, s[0:1]
	s_load_dwordx4 s[0:3], s[90:91], 0x70
	s_and_b32 s8, s37, 7
	v_lshlrev_b32_e32 v0, 2, v66
	s_lshl_b32 s9, s8, 16
	v_and_b32_e32 v2, 0x7c, v0
	s_waitcnt lgkmcnt(0)
	s_add_u32 s2, s2, s9
	v_ashrrev_i32_e32 v6, 5, v64
	s_addc_u32 s3, s3, 0
	v_lshlrev_b32_e32 v16, 2, v2
	v_lshlrev_b32_e32 v4, 7, v6
	v_lshl_add_u64 v[0:1], s[2:3], 0, v[16:17]
	v_ashrrev_i32_e32 v5, 31, v4
	v_lshl_add_u64 v[4:5], v[4:5], 2, v[0:1]
	global_load_dwordx4 v[8:11], v[4:5], off
	v_mov_b32_e32 v70, 0x2000
	v_mov_b32_e32 v71, 0
	v_lshl_add_u64 v[68:69], v[4:5], 0, v[70:71]
	global_load_dwordx4 v[72:75], v[68:69], off
	v_lshl_add_u64 v[68:69], v[68:69], 0, v[70:71]
	global_load_dwordx4 v[76:79], v[68:69], off
	v_lshl_add_u64 v[68:69], v[68:69], 0, v[70:71]
	global_load_dwordx4 v[80:83], v[68:69], off
	v_lshl_add_u64 v[68:69], v[68:69], 0, v[70:71]
	global_load_dwordx4 v[84:87], v[68:69], off
	v_lshl_add_u64 v[68:69], v[68:69], 0, v[70:71]
	global_load_dwordx4 v[88:91], v[68:69], off
	v_lshl_add_u64 v[68:69], v[68:69], 0, v[70:71]
	global_load_dwordx4 v[92:95], v[68:69], off
	v_lshl_add_u64 v[68:69], v[68:69], 0, v[70:71]
	global_load_dwordx4 v[96:99], v[68:69], off
	v_cmp_gt_i32_e32 vcc, v2, v6
	v_mov_b32_e32 v4, s17
	s_movk_i32 s3, 0x120
	v_lshlrev_b32_e32 v7, 1, v2
	v_mov_b32_e32 v12, s17
	v_and_b32_e32 v22, 0x7f, v64
	v_lshlrev_b32_e32 v16, 11, v22
	v_ashrrev_i32_e32 v28, 4, v64
	s_lshl_b32 s16, s8, 8
	v_and_b32_e32 v14, -8, v28
	v_ashrrev_i32_e32 v15, 31, v14
	s_lshl_b32 s2, s8, 9
	s_add_u32 s0, s0, s2
	s_addc_u32 s1, s1, 0
	v_lshl_add_u64 v[26:27], v[14:15], 2, s[0:1]
	s_waitcnt vmcnt(7)
	v_cndmask_b32_e32 v3, v8, v4, vcc
	v_cmp_lt_i32_e32 vcc, v2, v6
	v_or_b32_e32 v4, 3, v2
	s_nop 0
	v_cndmask_b32_e32 v5, v3, v8, vcc
	v_cndmask_b32_e32 v8, 0, v9, vcc
	v_or_b32_e32 v3, 2, v2
	v_cmp_le_i32_e32 vcc, v3, v6
	v_cvt_pk_bf16_f32 v8, v5, v8
	v_mul_lo_u32 v5, v6, s3
	v_add3_u32 v5, v60, v7, v5
	v_cndmask_b32_e32 v9, 0, v10, vcc
	v_cmp_le_i32_e32 vcc, v4, v6
	v_add_u32_e32 v7, 16, v6
	s_nop 0
	v_cndmask_b32_e32 v10, 0, v11, vcc
	v_cvt_pk_bf16_f32 v9, v9, v10
	ds_write_b64 v5, v[8:9]
	v_cmp_gt_i32_e32 vcc, v2, v7
	s_waitcnt vmcnt(6)
	v_mov_b32_e32 v8, v72
	v_mov_b32_e32 v9, v73
	v_mov_b32_e32 v10, v74
	v_mov_b32_e32 v11, v75
	s_nop 0
	v_cndmask_b32_e32 v12, v8, v12, vcc
	v_cmp_lt_i32_e32 vcc, v2, v7
	s_nop 1
	v_cndmask_b32_e32 v8, v12, v8, vcc
	v_cndmask_b32_e32 v9, 0, v9, vcc
	v_cmp_le_i32_e32 vcc, v3, v7
	v_cvt_pk_bf16_f32 v8, v8, v9
	v_mov_b32_e32 v12, s17
	s_nop 0
	v_cndmask_b32_e32 v10, 0, v10, vcc
	v_cmp_le_i32_e32 vcc, v4, v7
	s_nop 1
	v_cndmask_b32_e32 v7, 0, v11, vcc
	v_cvt_pk_bf16_f32 v9, v10, v7
	v_add_u32_e32 v7, 32, v6
	ds_write_b64 v5, v[8:9] offset:4608
	v_cmp_gt_i32_e32 vcc, v2, v7
	s_waitcnt vmcnt(5)
	v_mov_b32_e32 v8, v76
	v_mov_b32_e32 v9, v77
	v_mov_b32_e32 v10, v78
	v_mov_b32_e32 v11, v79
	s_nop 0
	v_cndmask_b32_e32 v12, v8, v12, vcc
	v_cmp_lt_i32_e32 vcc, v2, v7
	s_nop 1
	v_cndmask_b32_e32 v8, v12, v8, vcc
	v_cndmask_b32_e32 v9, 0, v9, vcc
	v_cmp_le_i32_e32 vcc, v3, v7
	v_cvt_pk_bf16_f32 v8, v8, v9
	v_mov_b32_e32 v12, s17
	s_nop 0
	v_cndmask_b32_e32 v10, 0, v10, vcc
	v_cmp_le_i32_e32 vcc, v4, v7
	s_nop 1
	v_cndmask_b32_e32 v7, 0, v11, vcc
	v_cvt_pk_bf16_f32 v9, v10, v7
	v_add_u32_e32 v7, 48, v6
	ds_write_b64 v5, v[8:9] offset:9216
	v_cmp_gt_i32_e32 vcc, v2, v7
	s_waitcnt vmcnt(4)
	v_mov_b32_e32 v8, v80
	v_mov_b32_e32 v9, v81
	v_mov_b32_e32 v10, v82
	v_mov_b32_e32 v11, v83
	s_nop 0
	v_cndmask_b32_e32 v12, v8, v12, vcc
	v_cmp_lt_i32_e32 vcc, v2, v7
	s_nop 1
	v_cndmask_b32_e32 v8, v12, v8, vcc
	v_cndmask_b32_e32 v9, 0, v9, vcc
	v_cmp_le_i32_e32 vcc, v3, v7
	v_cvt_pk_bf16_f32 v8, v8, v9
	v_mov_b32_e32 v12, s17
	s_nop 0
	v_cndmask_b32_e32 v10, 0, v10, vcc
	v_cmp_le_i32_e32 vcc, v4, v7
	s_nop 1
	v_cndmask_b32_e32 v7, 0, v11, vcc
	v_cvt_pk_bf16_f32 v9, v10, v7
	v_add_u32_e32 v7, 64, v6
	ds_write_b64 v5, v[8:9] offset:13824
	v_cmp_gt_i32_e32 vcc, v2, v7
	s_waitcnt vmcnt(3)
	v_mov_b32_e32 v8, v84
	v_mov_b32_e32 v9, v85
	v_mov_b32_e32 v10, v86
	v_mov_b32_e32 v11, v87
	s_nop 0
	v_cndmask_b32_e32 v12, v8, v12, vcc
	v_cmp_lt_i32_e32 vcc, v2, v7
	s_nop 1
	v_cndmask_b32_e32 v8, v12, v8, vcc
	v_cndmask_b32_e32 v9, 0, v9, vcc
	v_cmp_le_i32_e32 vcc, v3, v7
	v_cvt_pk_bf16_f32 v8, v8, v9
	v_mov_b32_e32 v12, s17
	s_nop 0
	v_cndmask_b32_e32 v10, 0, v10, vcc
	v_cmp_le_i32_e32 vcc, v4, v7
	s_nop 1
	v_cndmask_b32_e32 v7, 0, v11, vcc
	v_cvt_pk_bf16_f32 v9, v10, v7
	v_add_u32_e32 v7, 0x50, v6
	ds_write_b64 v5, v[8:9] offset:18432
	v_cmp_gt_i32_e32 vcc, v2, v7
	s_waitcnt vmcnt(2)
	v_mov_b32_e32 v8, v88
	v_mov_b32_e32 v9, v89
	v_mov_b32_e32 v10, v90
	v_mov_b32_e32 v11, v91
	s_nop 0
	v_cndmask_b32_e32 v12, v8, v12, vcc
	v_cmp_lt_i32_e32 vcc, v2, v7
	s_nop 1
	v_cndmask_b32_e32 v8, v12, v8, vcc
	v_cndmask_b32_e32 v9, 0, v9, vcc
	v_cmp_le_i32_e32 vcc, v3, v7
	v_cvt_pk_bf16_f32 v8, v8, v9
	v_mov_b32_e32 v12, s17
	s_nop 0
	v_cndmask_b32_e32 v10, 0, v10, vcc
	v_cmp_le_i32_e32 vcc, v4, v7
	s_nop 1
	v_cndmask_b32_e32 v7, 0, v11, vcc
	v_cvt_pk_bf16_f32 v9, v10, v7
	v_add_u32_e32 v7, 0x60, v6
	ds_write_b64 v5, v[8:9] offset:23040
	v_cmp_gt_i32_e32 vcc, v2, v7
	s_waitcnt vmcnt(1)
	v_mov_b32_e32 v8, v92
	v_mov_b32_e32 v9, v93
	v_mov_b32_e32 v10, v94
	v_mov_b32_e32 v11, v95
	s_nop 0
	v_cndmask_b32_e32 v12, v8, v12, vcc
	v_cmp_lt_i32_e32 vcc, v2, v7
	s_nop 1
	v_cndmask_b32_e32 v8, v12, v8, vcc
	v_cndmask_b32_e32 v9, 0, v9, vcc
	v_cmp_le_i32_e32 vcc, v3, v7
	v_cvt_pk_bf16_f32 v8, v8, v9
	s_nop 1
	v_cndmask_b32_e32 v10, 0, v10, vcc
	v_cmp_le_i32_e32 vcc, v4, v7
	s_nop 1
	v_cndmask_b32_e32 v7, 0, v11, vcc
	v_cvt_pk_bf16_f32 v9, v10, v7
	v_add_u32_e32 v10, 0x70, v6
	v_lshlrev_b32_e32 v6, 7, v10
	v_ashrrev_i32_e32 v7, 31, v6
	v_lshl_add_u64 v[0:1], v[6:7], 2, v[0:1]
	ds_write_b64 v5, v[8:9] offset:27648
	v_cmp_gt_i32_e32 vcc, v2, v10
	v_mov_b32_e32 v0, s17
	s_waitcnt vmcnt(0)
	v_mov_b32_e32 v6, v96
	v_mov_b32_e32 v7, v97
	v_mov_b32_e32 v8, v98
	v_mov_b32_e32 v9, v99
	v_cndmask_b32_e32 v0, v6, v0, vcc
	v_cmp_lt_i32_e32 vcc, v2, v10
	s_nop 1
	v_cndmask_b32_e32 v0, v0, v6, vcc
	v_cndmask_b32_e32 v1, 0, v7, vcc
	v_cmp_le_i32_e32 vcc, v3, v10
	v_cvt_pk_bf16_f32 v0, v0, v1
	s_nop 1
	v_cndmask_b32_e32 v2, 0, v8, vcc
	v_cmp_le_i32_e32 vcc, v4, v10
	s_nop 1
	v_cndmask_b32_e32 v3, 0, v9, vcc
	v_cvt_pk_bf16_f32 v1, v2, v3
	v_lshl_add_u64 v[2:3], s[6:7], 0, v[16:17]
	v_lshl_add_u64 v[2:3], v[2:3], 0, s[16:17]
	ds_write_b64 v5, v[0:1] offset:32256
	v_lshl_add_u32 v0, v22, 2, v65
	v_lshl_add_u64 v[18:19], v[14:15], 1, v[2:3]
	s_waitcnt lgkmcnt(0)
	s_barrier
; #define LAS __attribute__((address_space(3)))
; __device__ __forceinline__ unsigned f2bf(float f) { unsigned u = __float_as_uint(f); u += 0x7FFFu + ((u >> 16) & 1u); return u >> 16; }
; __device__ __forceinline__ void mixA_unit(const Ctx& c, int l, int a) {
;     ...
;     {
;         const int sx = c.tid & 127, dg = c.tid >> 7;
;         const float mu = st_mean[sx], rs = st_rstd[sx];
;         u32x4 raw[4];
; #pragma unroll
;         for (int i = 0; i < 4; ++i) raw[i] = *(const u32x4*)(VA + (size_t)sx * 1024 + hh * 128 + dg * 8 + 32 * i);
; #pragma unroll
;         for (int i = 0; i < 4; ++i) {
;             const int d8 = dg * 8 + 32 * i;
;             float x[8]; unpack8(raw[i], x);
;             const float* gp = c.f(I_AVN) + l * 1024 + hh * 128 + d8; const f32x4 g0 = *(const f32x4*)gp, g1 = *(const f32x4*)(gp + 4);
; #pragma unroll
;             for (int e = 0; e < 8; ++e) ((LAS bf16*)vT)[(d8 + e) * 144 + sx] = (bf16)f2bf((x[e] - mu) * rs * (e < 4 ? g0[e & 3] : g1[e & 3]));
;         }
;     }
	ds_read2st64_b32 v[0:1], v0 offset1:2
	global_load_dwordx4 v[2:5], v[18:19], off
	global_load_dwordx4 v[6:9], v[18:19], off offset:64
	global_load_dwordx4 v[10:13], v[18:19], off offset:128
	s_nop 0
	global_load_dwordx4 v[18:21], v[18:19], off offset:192
	v_lshl_add_u32 v16, v22, 1, v63
	s_waitcnt vmcnt(3)
	v_lshlrev_b32_e32 v29, 16, v2
	v_and_b32_e32 v30, 0xffff0000, v2
	v_lshlrev_b32_e32 v31, 16, v3
	v_and_b32_e32 v32, 0xffff0000, v3
	v_lshlrev_b32_e32 v33, 16, v4
	v_and_b32_e32 v34, 0xffff0000, v4
	v_lshlrev_b32_e32 v35, 16, v5
	v_and_b32_e32 v36, 0xffff0000, v5
	global_load_dwordx4 v[2:5], v[26:27], off offset:16
	global_load_dwordx4 v[22:25], v[26:27], off
	global_load_dwordx4 v[72:75], v[26:27], off offset:144
	global_load_dwordx4 v[76:79], v[26:27], off offset:128
	global_load_dwordx4 v[80:83], v[26:27], off offset:272
	global_load_dwordx4 v[84:87], v[26:27], off offset:256
	global_load_dwordx4 v[88:91], v[26:27], off offset:400
	global_load_dwordx4 v[92:95], v[26:27], off offset:384
	s_waitcnt lgkmcnt(0)
	v_sub_f32_e32 v15, v29, v0
	v_mul_f32_e32 v15, v1, v15
	s_waitcnt vmcnt(10)
	v_and_b32_e32 v29, 0xffff0000, v9
	s_waitcnt vmcnt(6)
	v_mul_f32_e32 v15, v15, v22
	v_bfe_u32 v22, v15, 16, 1
	v_add3_u32 v22, v15, v22, s33
	v_mad_u64_u32 v[14:15], s[0:1], v14, s3, v[16:17]
	v_sub_f32_e32 v15, v30, v0
	v_mul_f32_e32 v15, v1, v15
	v_mul_f32_e32 v15, v15, v23
	ds_write_b16_d16_hi v14, v22
	v_bfe_u32 v22, v15, 16, 1
	v_add3_u32 v15, v15, v22, s33
	ds_write_b16_d16_hi v14, v15 offset:288
	v_sub_f32_e32 v15, v31, v0
	v_mul_f32_e32 v15, v1, v15
	v_mul_f32_e32 v15, v15, v24
	v_bfe_u32 v22, v15, 16, 1
	v_add3_u32 v15, v15, v22, s33
	ds_write_b16_d16_hi v14, v15 offset:576
	v_sub_f32_e32 v15, v32, v0
	v_mul_f32_e32 v15, v1, v15
	v_mul_f32_e32 v15, v15, v25
	v_bfe_u32 v22, v15, 16, 1
	v_add3_u32 v15, v15, v22, s33
	ds_write_b16_d16_hi v14, v15 offset:864
	v_sub_f32_e32 v15, v33, v0
	v_mul_f32_e32 v15, v1, v15
	v_mul_f32_e32 v2, v15, v2
	v_bfe_u32 v15, v2, 16, 1
	v_add3_u32 v2, v2, v15, s33
	ds_write_b16_d16_hi v14, v2 offset:1152
	v_sub_f32_e32 v2, v34, v0
	v_mul_f32_e32 v2, v1, v2
	v_mul_f32_e32 v2, v2, v3
	v_bfe_u32 v3, v2, 16, 1
	v_add3_u32 v2, v2, v3, s33
	ds_write_b16_d16_hi v14, v2 offset:1440
	v_sub_f32_e32 v2, v35, v0
	v_mul_f32_e32 v2, v1, v2
	v_mul_f32_e32 v2, v2, v4
	v_bfe_u32 v3, v2, 16, 1
	v_add3_u32 v2, v2, v3, s33
	ds_write_b16_d16_hi v14, v2 offset:1728
	v_sub_f32_e32 v2, v36, v0
	v_mul_f32_e32 v2, v1, v2
	v_mul_f32_e32 v2, v2, v5
	v_bfe_u32 v3, v2, 16, 1
	v_add3_u32 v4, v2, v3, s33
	v_or_b32_e32 v2, 7, v28
	v_mad_u64_u32 v[2:3], s[0:1], v2, s3, v[16:17]
	ds_write_b16_d16_hi v2, v4
	v_lshlrev_b32_e32 v15, 16, v6
	v_and_b32_e32 v16, 0xffff0000, v6
	v_lshlrev_b32_e32 v22, 16, v7
	v_and_b32_e32 v23, 0xffff0000, v7
	v_lshlrev_b32_e32 v24, 16, v8
	v_and_b32_e32 v25, 0xffff0000, v8
	v_lshlrev_b32_e32 v28, 16, v9
	v_sub_f32_e32 v15, v15, v0
	v_mul_f32_e32 v15, v1, v15
	v_and_b32_e32 v36, 15, v66
	v_readlane_b32 s0, v251, 40
	v_readlane_b32 s1, v251, 41
	s_waitcnt vmcnt(4)
	v_mov_b32_e32 v2, v72
	v_mov_b32_e32 v3, v73
	v_mov_b32_e32 v4, v74
	v_mov_b32_e32 v5, v75
	v_mov_b32_e32 v6, v76
	v_mov_b32_e32 v7, v77
	v_mov_b32_e32 v8, v78
	v_mov_b32_e32 v9, v79
	v_mul_f32_e32 v6, v15, v6
	v_bfe_u32 v15, v6, 16, 1
	v_add3_u32 v6, v6, v15, s33
	ds_write_b16_d16_hi v14, v6 offset:9216
	v_sub_f32_e32 v6, v16, v0
	v_mul_f32_e32 v6, v1, v6
	v_mul_f32_e32 v6, v6, v7
	v_bfe_u32 v7, v6, 16, 1
	v_add3_u32 v6, v6, v7, s33
	ds_write_b16_d16_hi v14, v6 offset:9504
	v_sub_f32_e32 v6, v22, v0
	v_mul_f32_e32 v6, v1, v6
	v_mul_f32_e32 v6, v6, v8
	v_bfe_u32 v7, v6, 16, 1
	v_add3_u32 v6, v6, v7, s33
	ds_write_b16_d16_hi v14, v6 offset:9792
	v_sub_f32_e32 v6, v23, v0
	v_mul_f32_e32 v6, v1, v6
	v_mul_f32_e32 v6, v6, v9
	v_bfe_u32 v7, v6, 16, 1
	v_add3_u32 v6, v6, v7, s33
	ds_write_b16_d16_hi v14, v6 offset:10080
	v_sub_f32_e32 v6, v24, v0
	v_mul_f32_e32 v6, v1, v6
	v_mul_f32_e32 v2, v6, v2
	v_bfe_u32 v6, v2, 16, 1
	v_add3_u32 v2, v2, v6, s33
	ds_write_b16_d16_hi v14, v2 offset:10368
	v_sub_f32_e32 v2, v25, v0
	v_mul_f32_e32 v2, v1, v2
	v_mul_f32_e32 v2, v2, v3
	v_bfe_u32 v3, v2, 16, 1
	v_add3_u32 v2, v2, v3, s33
	ds_write_b16_d16_hi v14, v2 offset:10656
	v_sub_f32_e32 v2, v28, v0
	v_mul_f32_e32 v2, v1, v2
	v_mul_f32_e32 v2, v2, v4
	v_bfe_u32 v3, v2, 16, 1
	v_add3_u32 v2, v2, v3, s33
	ds_write_b16_d16_hi v14, v2 offset:10944
	v_sub_f32_e32 v2, v29, v0
	v_mul_f32_e32 v2, v1, v2
	v_mul_f32_e32 v2, v2, v5
	v_bfe_u32 v3, v2, 16, 1
	v_add3_u32 v2, v2, v3, s33
	ds_write_b16_d16_hi v14, v2 offset:11232
	v_lshlrev_b32_e32 v15, 16, v10
	v_sub_f32_e32 v15, v15, v0
	v_mul_f32_e32 v15, v1, v15
	v_and_b32_e32 v10, 0xffff0000, v10
	v_lshlrev_b32_e32 v16, 16, v11
	v_and_b32_e32 v11, 0xffff0000, v11
	v_lshlrev_b32_e32 v22, 16, v12
	v_and_b32_e32 v12, 0xffff0000, v12
	v_lshlrev_b32_e32 v23, 16, v13
	v_and_b32_e32 v13, 0xffff0000, v13
	s_waitcnt vmcnt(2)
; #define LAS __attribute__((address_space(3)))
; __device__ __forceinline__ unsigned f2bf(float f) { unsigned u = __float_as_uint(f); u += 0x7FFFu + ((u >> 16) & 1u); return u >> 16; }
; __device__ __forceinline__ void mixA_unit(const Ctx& c, int l, int a) {
;     ...
;         for (int i = 0; i < 4; ++i) {
;             const int d8 = dg * 8 + 32 * i;
;             float x[8]; unpack8(raw[i], x);
;             const float* gp = c.f(I_AVN) + l * 1024 + hh * 128 + d8; const f32x4 g0 = *(const f32x4*)gp, g1 = *(const f32x4*)(gp + 4);
; #pragma unroll
;             for (int e = 0; e < 8; ++e) ((LAS bf16*)vT)[(d8 + e) * 144 + sx] = (bf16)f2bf((x[e] - mu) * rs * (e < 4 ? g0[e & 3] : g1[e & 3]));
;         }
;     }
;     __syncthreads();
;     {
;         f32x4 acc[8];
; #pragma unroll
;         for (int dt = 0; dt < 8; ++dt) acc[dt] = (f32x4){0.f, 0.f, 0.f, 0.f};
;         const int nk = (wave >> 1) + 1;
; #pragma unroll
;         for (int kq = 0; kq < 4; ++kq) {
;             if (kq < nk) {
;                 const bf16x8 af = *(const LAS bf16x8*)(WmB + (wave * 16 + m) * 288 + kq * 64 + quad * 16);
;                 bf16x8 bfr[8];
; #pragma unroll
;                 for (int dt = 0; dt < 8; ++dt) bfr[dt] = *(const LAS bf16x8*)(vT + (dt * 16 + m) * 288 + kq * 64 + quad * 16);
; #pragma unroll
;                 for (int dt = 0; dt < 8; ++dt) acc[dt] = __builtin_amdgcn_mfma_f32_16x16x32_bf16(af, bfr[dt], acc[dt], 0, 0, 0);
;             }
;         }
	v_mov_b32_e32 v2, v80
	v_mov_b32_e32 v3, v81
	v_mov_b32_e32 v4, v82
	v_mov_b32_e32 v5, v83
	v_mov_b32_e32 v6, v84
	v_mov_b32_e32 v7, v85
	v_mov_b32_e32 v8, v86
	v_mov_b32_e32 v9, v87
	v_mul_f32_e32 v6, v15, v6
	v_bfe_u32 v15, v6, 16, 1
	v_add3_u32 v6, v6, v15, s33
	ds_write_b16_d16_hi v14, v6 offset:18432
	v_sub_f32_e32 v6, v10, v0
	v_mul_f32_e32 v6, v1, v6
	v_mul_f32_e32 v6, v6, v7
	v_bfe_u32 v7, v6, 16, 1
	v_add3_u32 v6, v6, v7, s33
	ds_write_b16_d16_hi v14, v6 offset:18720
	v_sub_f32_e32 v6, v16, v0
	v_mul_f32_e32 v6, v1, v6
	v_mul_f32_e32 v6, v6, v8
	v_bfe_u32 v7, v6, 16, 1
	v_add3_u32 v6, v6, v7, s33
	ds_write_b16_d16_hi v14, v6 offset:19008
	v_sub_f32_e32 v6, v11, v0
	v_mul_f32_e32 v6, v1, v6
	v_mul_f32_e32 v6, v6, v9
	v_bfe_u32 v7, v6, 16, 1
	v_add3_u32 v6, v6, v7, s33
	ds_write_b16_d16_hi v14, v6 offset:19296
	v_sub_f32_e32 v6, v22, v0
	v_mul_f32_e32 v6, v1, v6
	v_mul_f32_e32 v2, v6, v2
	v_bfe_u32 v6, v2, 16, 1
	v_add3_u32 v2, v2, v6, s33
	ds_write_b16_d16_hi v14, v2 offset:19584
	v_sub_f32_e32 v2, v12, v0
	v_mul_f32_e32 v2, v1, v2
	v_mul_f32_e32 v2, v2, v3
	v_bfe_u32 v3, v2, 16, 1
	v_add3_u32 v2, v2, v3, s33
	ds_write_b16_d16_hi v14, v2 offset:19872
	v_sub_f32_e32 v2, v23, v0
	v_mul_f32_e32 v2, v1, v2
	v_mul_f32_e32 v2, v2, v4
	v_bfe_u32 v3, v2, 16, 1
	v_add3_u32 v2, v2, v3, s33
	ds_write_b16_d16_hi v14, v2 offset:20160
	v_sub_f32_e32 v2, v13, v0
	v_mul_f32_e32 v2, v1, v2
	v_mul_f32_e32 v2, v2, v5
	v_bfe_u32 v3, v2, 16, 1
	v_add3_u32 v2, v2, v3, s33
	ds_write_b16_d16_hi v14, v2 offset:20448
	v_lshlrev_b32_e32 v10, 16, v18
	v_sub_f32_e32 v10, v10, v0
	v_mul_f32_e32 v10, v1, v10
	v_and_b32_e32 v11, 0xffff0000, v18
	v_lshlrev_b32_e32 v12, 16, v19
	v_and_b32_e32 v13, 0xffff0000, v19
	v_lshlrev_b32_e32 v15, 16, v20
	v_and_b32_e32 v16, 0xffff0000, v20
	v_lshlrev_b32_e32 v18, 16, v21
	v_and_b32_e32 v19, 0xffff0000, v21
	s_waitcnt vmcnt(0)
	v_mov_b32_e32 v2, v88
	v_mov_b32_e32 v3, v89
	v_mov_b32_e32 v4, v90
	v_mov_b32_e32 v5, v91
	v_mov_b32_e32 v6, v92
	v_mov_b32_e32 v7, v93
	v_mov_b32_e32 v8, v94
	v_mov_b32_e32 v9, v95
	v_mul_f32_e32 v6, v10, v6
	v_bfe_u32 v10, v6, 16, 1
	v_add3_u32 v6, v6, v10, s33
	ds_write_b16_d16_hi v14, v6 offset:27648
	v_sub_f32_e32 v6, v11, v0
	v_mul_f32_e32 v6, v1, v6
	v_mul_f32_e32 v6, v6, v7
	v_bfe_u32 v7, v6, 16, 1
	v_add3_u32 v6, v6, v7, s33
	ds_write_b16_d16_hi v14, v6 offset:27936
	v_sub_f32_e32 v6, v12, v0
	v_mul_f32_e32 v6, v1, v6
	v_mul_f32_e32 v6, v6, v8
	v_bfe_u32 v7, v6, 16, 1
	v_add3_u32 v6, v6, v7, s33
	ds_write_b16_d16_hi v14, v6 offset:28224
	v_sub_f32_e32 v6, v13, v0
	v_mul_f32_e32 v6, v1, v6
	v_mul_f32_e32 v6, v6, v9
	v_bfe_u32 v7, v6, 16, 1
	v_add3_u32 v6, v6, v7, s33
	ds_write_b16_d16_hi v14, v6 offset:28512
	v_sub_f32_e32 v6, v15, v0
	v_mul_f32_e32 v6, v1, v6
	v_mul_f32_e32 v2, v6, v2
	v_bfe_u32 v6, v2, 16, 1
	v_add3_u32 v2, v2, v6, s33
	ds_write_b16_d16_hi v14, v2 offset:28800
	v_sub_f32_e32 v2, v16, v0
	v_mul_f32_e32 v2, v1, v2
	v_mul_f32_e32 v2, v2, v3
	v_bfe_u32 v3, v2, 16, 1
	v_add3_u32 v2, v2, v3, s33
	ds_write_b16_d16_hi v14, v2 offset:29088
	v_sub_f32_e32 v2, v18, v0
	v_sub_f32_e32 v0, v19, v0
	v_mul_f32_e32 v0, v1, v0
	v_mul_f32_e32 v2, v1, v2
	v_mul_f32_e32 v0, v0, v5
	v_mul_f32_e32 v2, v2, v4
	v_bfe_u32 v1, v0, 16, 1
	v_bfe_u32 v3, v2, 16, 1
	v_add3_u32 v0, v0, v1, s33
	v_add3_u32 v2, v2, v3, s33
	ds_write_b16_d16_hi v14, v0 offset:29664
	v_or_b32_e32 v0, s0, v36
	ds_write_b16_d16_hi v14, v2 offset:29376
	v_mad_u64_u32 v[2:3], s[0:1], v0, s3, v[60:61]
	v_and_b32_e32 v1, -16, v66
	v_readlane_b32 s0, v251, 12
	v_add_u32_e32 v0, v63, v1
	v_readlane_b32 s1, v251, 13
	s_andn2_b64 vcc, exec, s[0:1]
	v_add_u32_e32 v37, v2, v1
	v_mad_u32_u24 v38, v36, s3, v0
	s_waitcnt lgkmcnt(0)
	s_barrier
	s_cbranch_vccnz .LBB0_1078
	ds_read_b128 v[0:3], v37
	ds_read_b128 v[4:7], v38
	ds_read_b128 v[8:11], v38 offset:4608
	s_waitcnt lgkmcnt(1)
	v_mfma_f32_16x16x32_bf16 v[32:35], v[0:3], v[4:7], 0
	s_waitcnt lgkmcnt(0)
	v_mfma_f32_16x16x32_bf16 v[28:31], v[0:3], v[8:11], 0
	ds_read_b128 v[4:7], v38 offset:9216
	ds_read_b128 v[8:11], v38 offset:13824
	s_waitcnt lgkmcnt(1)
	v_mfma_f32_16x16x32_bf16 v[24:27], v[0:3], v[4:7], 0
	s_waitcnt lgkmcnt(0)
	v_mfma_f32_16x16x32_bf16 v[20:23], v[0:3], v[8:11], 0
	ds_read_b128 v[4:7], v38 offset:18432
	ds_read_b128 v[8:11], v38 offset:23040
	s_waitcnt lgkmcnt(1)
	v_mfma_f32_16x16x32_bf16 v[12:15], v[0:3], v[4:7], 0
	ds_read_b128 v[4:7], v38 offset:27648
	ds_read_b128 v[40:43], v38 offset:32256
	s_waitcnt lgkmcnt(2)
	v_mfma_f32_16x16x32_bf16 v[8:11], v[0:3], v[8:11], 0
	s_waitcnt lgkmcnt(1)
	v_mfma_f32_16x16x32_bf16 v[4:7], v[0:3], v[4:7], 0
	s_waitcnt lgkmcnt(0)
	v_mfma_f32_16x16x32_bf16 v[0:3], v[0:3], v[40:43], 0
	s_branch .LBB0_1079

; __device__ __forceinline__ unsigned cvt_pk_bf16(float lo, float hi) { unsigned r; asm volatile("v_cvt_pk_bf16_f32 %0, %1, %2" : "=v"(r) : "v"(lo), "v"(hi)); return r; }
; #define LAS __attribute__((address_space(3)))
;     template <class T> __device__ __forceinline__ T* w(size_t off) const { return (T*)(pp->ws + off); }
; __device__ __forceinline__ void mixA_unit(const Ctx& c, int l, int a) {
;     ...
;         const int s4 = (c.tid & 31) * 4;
;         const float* wsrc = c.f(I_AWS) + (size_t)(l * 8 + hh) * 128 * 128;
; #pragma unroll
;         for (int i = 0; i < 8; ++i) {
;             const int t = (c.tid >> 5) + 16 * i;
;             f32x4 w = *(const f32x4*)(wsrc + t * 128 + s4);
; #pragma unroll
;             for (int e = 0; e < 4; ++e) if (s4 + e > t) w[e] = 0.f;
;             *(LAS u32x2*)(WmB + t * 288 + s4 * 2) = (u32x2){pg8::cvt_pk_bf16(w[0], w[1]), pg8::cvt_pk_bf16(w[2], w[3])};
;         }
;     }
;     __syncthreads();
.LBB0_2599:
	s_or_b64 exec, exec, s[0:1]
	s_load_dwordx4 s[0:3], s[90:91], 0x70
	s_and_b32 s9, s18, 7
	s_or_b32 s8, s9, 8
	v_lshlrev_b32_e32 v0, 2, v66
	s_lshl_b32 s11, s8, 16
	v_and_b32_e32 v2, 0x7c, v0
	s_waitcnt lgkmcnt(0)
	s_add_u32 s2, s2, s11
	v_ashrrev_i32_e32 v6, 5, v64
	s_addc_u32 s3, s3, 0
	v_lshlrev_b32_e32 v16, 2, v2
	v_lshlrev_b32_e32 v4, 7, v6
	v_lshl_add_u64 v[0:1], s[2:3], 0, v[16:17]
	v_ashrrev_i32_e32 v5, 31, v4
	v_lshl_add_u64 v[4:5], v[4:5], 2, v[0:1]
	global_load_dwordx4 v[8:11], v[4:5], off
	v_mov_b32_e32 v70, 0x2000
	v_mov_b32_e32 v71, 0
	v_lshl_add_u64 v[68:69], v[4:5], 0, v[70:71]
	global_load_dwordx4 v[72:75], v[68:69], off
	v_lshl_add_u64 v[68:69], v[68:69], 0, v[70:71]
	global_load_dwordx4 v[76:79], v[68:69], off
	v_lshl_add_u64 v[68:69], v[68:69], 0, v[70:71]
	global_load_dwordx4 v[80:83], v[68:69], off
	v_lshl_add_u64 v[68:69], v[68:69], 0, v[70:71]
	global_load_dwordx4 v[84:87], v[68:69], off
	v_lshl_add_u64 v[68:69], v[68:69], 0, v[70:71]
	global_load_dwordx4 v[88:91], v[68:69], off
	v_lshl_add_u64 v[68:69], v[68:69], 0, v[70:71]
	global_load_dwordx4 v[92:95], v[68:69], off
	v_lshl_add_u64 v[68:69], v[68:69], 0, v[70:71]
	global_load_dwordx4 v[96:99], v[68:69], off
	v_cmp_gt_i32_e32 vcc, v2, v6
	v_mov_b32_e32 v4, s15
	s_movk_i32 s3, 0x120
	v_lshlrev_b32_e32 v7, 1, v2
	v_mov_b32_e32 v12, s15
	v_and_b32_e32 v22, 0x7f, v64
	v_lshlrev_b32_e32 v16, 11, v22
	v_ashrrev_i32_e32 v28, 4, v64
	s_lshl_b32 s14, s9, 8
	v_and_b32_e32 v14, -8, v28
	v_ashrrev_i32_e32 v15, 31, v14
	s_lshl_b32 s2, s9, 9
	s_add_u32 s0, s0, s2
	s_addc_u32 s1, s1, 0
	s_waitcnt vmcnt(7)
	v_cndmask_b32_e32 v3, v8, v4, vcc
	v_cmp_lt_i32_e32 vcc, v2, v6
	v_or_b32_e32 v4, 3, v2
	s_nop 0
	v_cndmask_b32_e32 v5, v3, v8, vcc
	v_cndmask_b32_e32 v8, 0, v9, vcc
	v_or_b32_e32 v3, 2, v2
	v_cmp_le_i32_e32 vcc, v3, v6
	v_cvt_pk_bf16_f32 v8, v5, v8
	v_mul_lo_u32 v5, v6, s3
	v_add3_u32 v5, v60, v7, v5
	v_cndmask_b32_e32 v9, 0, v10, vcc
	v_cmp_le_i32_e32 vcc, v4, v6
	v_add_u32_e32 v7, 16, v6
	s_nop 0
	v_cndmask_b32_e32 v10, 0, v11, vcc
	v_cvt_pk_bf16_f32 v9, v9, v10
	ds_write_b64 v5, v[8:9]
	v_cmp_gt_i32_e32 vcc, v2, v7
	s_waitcnt vmcnt(6)
	v_mov_b32_e32 v8, v72
	v_mov_b32_e32 v9, v73
	v_mov_b32_e32 v10, v74
	v_mov_b32_e32 v11, v75
	s_nop 0
	v_cndmask_b32_e32 v12, v8, v12, vcc
	v_cmp_lt_i32_e32 vcc, v2, v7
	s_nop 1
	v_cndmask_b32_e32 v8, v12, v8, vcc
	v_cndmask_b32_e32 v9, 0, v9, vcc
	v_cmp_le_i32_e32 vcc, v3, v7
	v_cvt_pk_bf16_f32 v8, v8, v9
	v_mov_b32_e32 v12, s15
	s_nop 0
	v_cndmask_b32_e32 v10, 0, v10, vcc
	v_cmp_le_i32_e32 vcc, v4, v7
	s_nop 1
	v_cndmask_b32_e32 v7, 0, v11, vcc
	v_cvt_pk_bf16_f32 v9, v10, v7
	v_add_u32_e32 v7, 32, v6
	ds_write_b64 v5, v[8:9] offset:4608
	v_cmp_gt_i32_e32 vcc, v2, v7
	s_waitcnt vmcnt(5)
	v_mov_b32_e32 v8, v76
	v_mov_b32_e32 v9, v77
	v_mov_b32_e32 v10, v78
	v_mov_b32_e32 v11, v79
	s_nop 0
	v_cndmask_b32_e32 v12, v8, v12, vcc
	v_cmp_lt_i32_e32 vcc, v2, v7
	s_nop 1
	v_cndmask_b32_e32 v8, v12, v8, vcc
	v_cndmask_b32_e32 v9, 0, v9, vcc
	v_cmp_le_i32_e32 vcc, v3, v7
	v_cvt_pk_bf16_f32 v8, v8, v9
	v_mov_b32_e32 v12, s15
	s_nop 0
	v_cndmask_b32_e32 v10, 0, v10, vcc
	v_cmp_le_i32_e32 vcc, v4, v7
	s_nop 1
	v_cndmask_b32_e32 v7, 0, v11, vcc
	v_cvt_pk_bf16_f32 v9, v10, v7
	v_add_u32_e32 v7, 48, v6
	ds_write_b64 v5, v[8:9] offset:9216
	v_cmp_gt_i32_e32 vcc, v2, v7
	s_waitcnt vmcnt(4)
	v_mov_b32_e32 v8, v80
	v_mov_b32_e32 v9, v81
	v_mov_b32_e32 v10, v82
	v_mov_b32_e32 v11, v83
	s_nop 0
	v_cndmask_b32_e32 v12, v8, v12, vcc
	v_cmp_lt_i32_e32 vcc, v2, v7
	s_nop 1
	v_cndmask_b32_e32 v8, v12, v8, vcc
	v_cndmask_b32_e32 v9, 0, v9, vcc
	v_cmp_le_i32_e32 vcc, v3, v7
	v_cvt_pk_bf16_f32 v8, v8, v9
	v_mov_b32_e32 v12, s15
	s_nop 0
	v_cndmask_b32_e32 v10, 0, v10, vcc
	v_cmp_le_i32_e32 vcc, v4, v7
	s_nop 1
	v_cndmask_b32_e32 v7, 0, v11, vcc
	v_cvt_pk_bf16_f32 v9, v10, v7
	v_add_u32_e32 v7, 64, v6
	ds_write_b64 v5, v[8:9] offset:13824
	v_cmp_gt_i32_e32 vcc, v2, v7
	s_waitcnt vmcnt(3)
	v_mov_b32_e32 v8, v84
	v_mov_b32_e32 v9, v85
	v_mov_b32_e32 v10, v86
	v_mov_b32_e32 v11, v87
	s_nop 0
	v_cndmask_b32_e32 v12, v8, v12, vcc
	v_cmp_lt_i32_e32 vcc, v2, v7
	s_nop 1
	v_cndmask_b32_e32 v8, v12, v8, vcc
	v_cndmask_b32_e32 v9, 0, v9, vcc
	v_cmp_le_i32_e32 vcc, v3, v7
	v_cvt_pk_bf16_f32 v8, v8, v9
	v_mov_b32_e32 v12, s15
	s_nop 0
	v_cndmask_b32_e32 v10, 0, v10, vcc
	v_cmp_le_i32_e32 vcc, v4, v7
	s_nop 1
	v_cndmask_b32_e32 v7, 0, v11, vcc
	v_cvt_pk_bf16_f32 v9, v10, v7
	v_add_u32_e32 v7, 0x50, v6
	ds_write_b64 v5, v[8:9] offset:18432
	v_cmp_gt_i32_e32 vcc, v2, v7
	s_waitcnt vmcnt(2)
	v_mov_b32_e32 v8, v88
	v_mov_b32_e32 v9, v89
	v_mov_b32_e32 v10, v90
	v_mov_b32_e32 v11, v91
	s_nop 0
	v_cndmask_b32_e32 v12, v8, v12, vcc
	v_cmp_lt_i32_e32 vcc, v2, v7
	s_nop 1
	v_cndmask_b32_e32 v8, v12, v8, vcc
	v_cndmask_b32_e32 v9, 0, v9, vcc
	v_cmp_le_i32_e32 vcc, v3, v7
	v_cvt_pk_bf16_f32 v8, v8, v9
	v_mov_b32_e32 v12, s15
	s_nop 0
	v_cndmask_b32_e32 v10, 0, v10, vcc
	v_cmp_le_i32_e32 vcc, v4, v7
	s_nop 1
	v_cndmask_b32_e32 v7, 0, v11, vcc
	v_cvt_pk_bf16_f32 v9, v10, v7
	v_add_u32_e32 v7, 0x60, v6
	ds_write_b64 v5, v[8:9] offset:23040
	v_cmp_gt_i32_e32 vcc, v2, v7
	s_waitcnt vmcnt(1)
	v_mov_b32_e32 v8, v92
	v_mov_b32_e32 v9, v93
	v_mov_b32_e32 v10, v94
	v_mov_b32_e32 v11, v95
	s_nop 0
	v_cndmask_b32_e32 v12, v8, v12, vcc
	v_cmp_lt_i32_e32 vcc, v2, v7
	s_nop 1
	v_cndmask_b32_e32 v8, v12, v8, vcc
	v_cndmask_b32_e32 v9, 0, v9, vcc
	v_cmp_le_i32_e32 vcc, v3, v7
	v_cvt_pk_bf16_f32 v8, v8, v9
	s_nop 1
	v_cndmask_b32_e32 v10, 0, v10, vcc
	v_cmp_le_i32_e32 vcc, v4, v7
	s_nop 1
	v_cndmask_b32_e32 v7, 0, v11, vcc
	v_cvt_pk_bf16_f32 v9, v10, v7
	v_add_u32_e32 v10, 0x70, v6
	v_lshlrev_b32_e32 v6, 7, v10
	v_ashrrev_i32_e32 v7, 31, v6
	v_lshl_add_u64 v[0:1], v[6:7], 2, v[0:1]
	ds_write_b64 v5, v[8:9] offset:27648
	v_cmp_gt_i32_e32 vcc, v2, v10
	v_mov_b32_e32 v0, s15
	s_waitcnt vmcnt(0)
	v_mov_b32_e32 v6, v96
	v_mov_b32_e32 v7, v97
	v_mov_b32_e32 v8, v98
	v_mov_b32_e32 v9, v99
	v_cndmask_b32_e32 v0, v6, v0, vcc
	v_cmp_lt_i32_e32 vcc, v2, v10
	s_nop 1
	v_cndmask_b32_e32 v0, v0, v6, vcc
	v_cndmask_b32_e32 v1, 0, v7, vcc
	v_cmp_le_i32_e32 vcc, v3, v10
	v_cvt_pk_bf16_f32 v0, v0, v1
	s_nop 1
	v_cndmask_b32_e32 v2, 0, v8, vcc
	v_cmp_le_i32_e32 vcc, v4, v10
	s_nop 1
	v_cndmask_b32_e32 v3, 0, v9, vcc
	v_cvt_pk_bf16_f32 v1, v2, v3
	v_lshl_add_u64 v[2:3], s[6:7], 0, v[16:17]
	v_lshl_add_u64 v[2:3], v[2:3], 0, s[14:15]
	ds_write_b64 v5, v[0:1] offset:32256
	v_lshl_add_u32 v0, v22, 2, v65
	v_lshl_add_u64 v[18:19], v[14:15], 1, v[2:3]
	s_waitcnt lgkmcnt(0)
	s_barrier
; #define LAS __attribute__((address_space(3)))
; __device__ __forceinline__ unsigned f2bf(float f) { unsigned u = __float_as_uint(f); u += 0x7FFFu + ((u >> 16) & 1u); return u >> 16; }
; __device__ __forceinline__ void mixA_unit(const Ctx& c, int l, int a) {
;     ...
;     {
;         const int sx = c.tid & 127, dg = c.tid >> 7;
;         const float mu = st_mean[sx], rs = st_rstd[sx];
;         u32x4 raw[4];
; #pragma unroll
;         for (int i = 0; i < 4; ++i) raw[i] = *(const u32x4*)(VA + (size_t)sx * 1024 + hh * 128 + dg * 8 + 32 * i);
; #pragma unroll
;         for (int i = 0; i < 4; ++i) {
;             const int d8 = dg * 8 + 32 * i;
;             float x[8]; unpack8(raw[i], x);
;             const float* gp = c.f(I_AVN) + l * 1024 + hh * 128 + d8; const f32x4 g0 = *(const f32x4*)gp, g1 = *(const f32x4*)(gp + 4);
; #pragma unroll
;             for (int e = 0; e < 8; ++e) ((LAS bf16*)vT)[(d8 + e) * 144 + sx] = (bf16)f2bf((x[e] - mu) * rs * (e < 4 ? g0[e & 3] : g1[e & 3]));
;         }
;     }
	ds_read2st64_b32 v[0:1], v0 offset1:2
	global_load_dwordx4 v[2:5], v[18:19], off
	global_load_dwordx4 v[6:9], v[18:19], off offset:64
	global_load_dwordx4 v[10:13], v[18:19], off offset:128
	s_nop 0
	global_load_dwordx4 v[18:21], v[18:19], off offset:192
	v_lshl_add_u32 v16, v22, 1, v63
	s_waitcnt vmcnt(3)
	v_lshlrev_b32_e32 v29, 16, v2
	v_and_b32_e32 v30, 0xffff0000, v2
	v_lshlrev_b32_e32 v31, 16, v3
	v_and_b32_e32 v32, 0xffff0000, v3
	v_lshl_add_u64 v[2:3], v[14:15], 2, s[0:1]
	s_movk_i32 s0, 0x1000
	v_lshl_add_u64 v[26:27], v[2:3], 0, s[22:23]
	v_add_co_u32_e32 v2, vcc, s0, v2
	v_lshlrev_b32_e32 v33, 16, v4
	s_nop 0
	v_addc_co_u32_e32 v3, vcc, 0, v3, vcc
	v_and_b32_e32 v34, 0xffff0000, v4
	v_lshlrev_b32_e32 v35, 16, v5
	v_and_b32_e32 v36, 0xffff0000, v5
	global_load_dwordx4 v[2:5], v[2:3], off
	s_nop 0
	global_load_dwordx4 v[22:25], v[26:27], off offset:16
	global_load_dwordx4 v[72:75], v[26:27], off offset:144
	global_load_dwordx4 v[76:79], v[26:27], off offset:128
	global_load_dwordx4 v[80:83], v[26:27], off offset:272
	global_load_dwordx4 v[84:87], v[26:27], off offset:256
	global_load_dwordx4 v[88:91], v[26:27], off offset:400
	global_load_dwordx4 v[92:95], v[26:27], off offset:384
	s_waitcnt lgkmcnt(0)
	v_sub_f32_e32 v15, v29, v0
	v_mul_f32_e32 v15, v1, v15
	s_waitcnt vmcnt(10)
	v_and_b32_e32 v29, 0xffff0000, v9
	s_waitcnt vmcnt(7)
	v_mul_f32_e32 v2, v15, v2
	v_bfe_u32 v15, v2, 16, 1
	v_add3_u32 v2, v2, v15, s33
	v_mad_u64_u32 v[14:15], s[0:1], v14, s3, v[16:17]
	ds_write_b16_d16_hi v14, v2
	v_sub_f32_e32 v2, v30, v0
	v_mul_f32_e32 v2, v1, v2
	v_mul_f32_e32 v2, v2, v3
	v_bfe_u32 v3, v2, 16, 1
	v_add3_u32 v2, v2, v3, s33
	ds_write_b16_d16_hi v14, v2 offset:288
	v_sub_f32_e32 v2, v31, v0
	v_mul_f32_e32 v2, v1, v2
	v_mul_f32_e32 v2, v2, v4
	v_bfe_u32 v3, v2, 16, 1
	v_add3_u32 v2, v2, v3, s33
	ds_write_b16_d16_hi v14, v2 offset:576
	v_sub_f32_e32 v2, v32, v0
	v_mul_f32_e32 v2, v1, v2
	v_mul_f32_e32 v2, v2, v5
	v_bfe_u32 v3, v2, 16, 1
	v_add3_u32 v2, v2, v3, s33
	ds_write_b16_d16_hi v14, v2 offset:864
	v_sub_f32_e32 v2, v33, v0
	v_mul_f32_e32 v2, v1, v2
	s_waitcnt vmcnt(6)
	v_mul_f32_e32 v2, v2, v22
	v_bfe_u32 v3, v2, 16, 1
	v_add3_u32 v2, v2, v3, s33
	ds_write_b16_d16_hi v14, v2 offset:1152
	v_sub_f32_e32 v2, v34, v0
	v_mul_f32_e32 v2, v1, v2
	v_mul_f32_e32 v2, v2, v23
	v_bfe_u32 v3, v2, 16, 1
	v_add3_u32 v2, v2, v3, s33
	ds_write_b16_d16_hi v14, v2 offset:1440
	v_sub_f32_e32 v2, v35, v0
	v_mul_f32_e32 v2, v1, v2
	v_mul_f32_e32 v2, v2, v24
	v_bfe_u32 v3, v2, 16, 1
	v_add3_u32 v2, v2, v3, s33
	ds_write_b16_d16_hi v14, v2 offset:1728
	v_sub_f32_e32 v2, v36, v0
	v_mul_f32_e32 v2, v1, v2
	v_mul_f32_e32 v2, v2, v25
	v_bfe_u32 v3, v2, 16, 1
	v_add3_u32 v4, v2, v3, s33
	v_or_b32_e32 v2, 7, v28
	v_mad_u64_u32 v[2:3], s[0:1], v2, s3, v[16:17]
	ds_write_b16_d16_hi v2, v4
	v_lshlrev_b32_e32 v15, 16, v6
	v_and_b32_e32 v16, 0xffff0000, v6
	v_lshlrev_b32_e32 v22, 16, v7
	v_and_b32_e32 v23, 0xffff0000, v7
	v_lshlrev_b32_e32 v24, 16, v8
	v_and_b32_e32 v25, 0xffff0000, v8
	v_lshlrev_b32_e32 v28, 16, v9
	v_sub_f32_e32 v15, v15, v0
	v_mul_f32_e32 v15, v1, v15
	v_and_b32_e32 v36, 15, v66
	v_readlane_b32 s0, v251, 40
	v_readlane_b32 s1, v251, 41
	s_waitcnt vmcnt(4)
	v_mov_b32_e32 v2, v72
	v_mov_b32_e32 v3, v73
	v_mov_b32_e32 v4, v74
	v_mov_b32_e32 v5, v75
	v_mov_b32_e32 v6, v76
	v_mov_b32_e32 v7, v77
	v_mov_b32_e32 v8, v78
	v_mov_b32_e32 v9, v79
	v_mul_f32_e32 v6, v15, v6
	v_bfe_u32 v15, v6, 16, 1
	v_add3_u32 v6, v6, v15, s33
	ds_write_b16_d16_hi v14, v6 offset:9216
	v_sub_f32_e32 v6, v16, v0
	v_mul_f32_e32 v6, v1, v6
	v_mul_f32_e32 v6, v6, v7
	v_bfe_u32 v7, v6, 16, 1
	v_add3_u32 v6, v6, v7, s33
	ds_write_b16_d16_hi v14, v6 offset:9504
	v_sub_f32_e32 v6, v22, v0
	v_mul_f32_e32 v6, v1, v6
	v_mul_f32_e32 v6, v6, v8
	v_bfe_u32 v7, v6, 16, 1
	v_add3_u32 v6, v6, v7, s33
	ds_write_b16_d16_hi v14, v6 offset:9792
	v_sub_f32_e32 v6, v23, v0
	v_mul_f32_e32 v6, v1, v6
	v_mul_f32_e32 v6, v6, v9
	v_bfe_u32 v7, v6, 16, 1
	v_add3_u32 v6, v6, v7, s33
	ds_write_b16_d16_hi v14, v6 offset:10080
	v_sub_f32_e32 v6, v24, v0
	v_mul_f32_e32 v6, v1, v6
	v_mul_f32_e32 v2, v6, v2
	v_bfe_u32 v6, v2, 16, 1
	v_add3_u32 v2, v2, v6, s33
	ds_write_b16_d16_hi v14, v2 offset:10368
	v_sub_f32_e32 v2, v25, v0
	v_mul_f32_e32 v2, v1, v2
	v_mul_f32_e32 v2, v2, v3
	v_bfe_u32 v3, v2, 16, 1
	v_add3_u32 v2, v2, v3, s33
	ds_write_b16_d16_hi v14, v2 offset:10656
	v_sub_f32_e32 v2, v28, v0
	v_mul_f32_e32 v2, v1, v2
	v_mul_f32_e32 v2, v2, v4
	v_bfe_u32 v3, v2, 16, 1
	v_add3_u32 v2, v2, v3, s33
	ds_write_b16_d16_hi v14, v2 offset:10944
	v_sub_f32_e32 v2, v29, v0
	v_mul_f32_e32 v2, v1, v2
	v_mul_f32_e32 v2, v2, v5
	v_bfe_u32 v3, v2, 16, 1
	v_add3_u32 v2, v2, v3, s33
	ds_write_b16_d16_hi v14, v2 offset:11232
	v_lshlrev_b32_e32 v15, 16, v10
	v_sub_f32_e32 v15, v15, v0
	v_mul_f32_e32 v15, v1, v15
	v_and_b32_e32 v10, 0xffff0000, v10
	v_lshlrev_b32_e32 v16, 16, v11
	v_and_b32_e32 v11, 0xffff0000, v11
	v_lshlrev_b32_e32 v22, 16, v12
	v_and_b32_e32 v12, 0xffff0000, v12
	v_lshlrev_b32_e32 v23, 16, v13
	v_and_b32_e32 v13, 0xffff0000, v13
	s_waitcnt vmcnt(2)
; #define LAS __attribute__((address_space(3)))
; __device__ __forceinline__ unsigned f2bf(float f) { unsigned u = __float_as_uint(f); u += 0x7FFFu + ((u >> 16) & 1u); return u >> 16; }
; __device__ __forceinline__ void mixA_unit(const Ctx& c, int l, int a) {
;     ...
;         for (int i = 0; i < 4; ++i) {
;             const int d8 = dg * 8 + 32 * i;
;             float x[8]; unpack8(raw[i], x);
;             const float* gp = c.f(I_AVN) + l * 1024 + hh * 128 + d8; const f32x4 g0 = *(const f32x4*)gp, g1 = *(const f32x4*)(gp + 4);
; #pragma unroll
;             for (int e = 0; e < 8; ++e) ((LAS bf16*)vT)[(d8 + e) * 144 + sx] = (bf16)f2bf((x[e] - mu) * rs * (e < 4 ? g0[e & 3] : g1[e & 3]));
;         }
;     }
;     __syncthreads();
;     {
;         f32x4 acc[8];
; #pragma unroll
;         for (int dt = 0; dt < 8; ++dt) acc[dt] = (f32x4){0.f, 0.f, 0.f, 0.f};
;         const int nk = (wave >> 1) + 1;
; #pragma unroll
;         for (int kq = 0; kq < 4; ++kq) {
;             if (kq < nk) {
;                 const bf16x8 af = *(const LAS bf16x8*)(WmB + (wave * 16 + m) * 288 + kq * 64 + quad * 16);
;                 bf16x8 bfr[8];
; #pragma unroll
;                 for (int dt = 0; dt < 8; ++dt) bfr[dt] = *(const LAS bf16x8*)(vT + (dt * 16 + m) * 288 + kq * 64 + quad * 16);
; #pragma unroll
;                 for (int dt = 0; dt < 8; ++dt) acc[dt] = __builtin_amdgcn_mfma_f32_16x16x32_bf16(af, bfr[dt], acc[dt], 0, 0, 0);
;             }
;         }
	v_mov_b32_e32 v2, v80
	v_mov_b32_e32 v3, v81
	v_mov_b32_e32 v4, v82
	v_mov_b32_e32 v5, v83
	v_mov_b32_e32 v6, v84
	v_mov_b32_e32 v7, v85
	v_mov_b32_e32 v8, v86
	v_mov_b32_e32 v9, v87
	v_mul_f32_e32 v6, v15, v6
	v_bfe_u32 v15, v6, 16, 1
	v_add3_u32 v6, v6, v15, s33
	ds_write_b16_d16_hi v14, v6 offset:18432
	v_sub_f32_e32 v6, v10, v0
	v_mul_f32_e32 v6, v1, v6
	v_mul_f32_e32 v6, v6, v7
	v_bfe_u32 v7, v6, 16, 1
	v_add3_u32 v6, v6, v7, s33
	ds_write_b16_d16_hi v14, v6 offset:18720
	v_sub_f32_e32 v6, v16, v0
	v_mul_f32_e32 v6, v1, v6
	v_mul_f32_e32 v6, v6, v8
	v_bfe_u32 v7, v6, 16, 1
	v_add3_u32 v6, v6, v7, s33
	ds_write_b16_d16_hi v14, v6 offset:19008
	v_sub_f32_e32 v6, v11, v0
	v_mul_f32_e32 v6, v1, v6
	v_mul_f32_e32 v6, v6, v9
	v_bfe_u32 v7, v6, 16, 1
	v_add3_u32 v6, v6, v7, s33
	ds_write_b16_d16_hi v14, v6 offset:19296
	v_sub_f32_e32 v6, v22, v0
	v_mul_f32_e32 v6, v1, v6
	v_mul_f32_e32 v2, v6, v2
	v_bfe_u32 v6, v2, 16, 1
	v_add3_u32 v2, v2, v6, s33
	ds_write_b16_d16_hi v14, v2 offset:19584
	v_sub_f32_e32 v2, v12, v0
	v_mul_f32_e32 v2, v1, v2
	v_mul_f32_e32 v2, v2, v3
	v_bfe_u32 v3, v2, 16, 1
	v_add3_u32 v2, v2, v3, s33
	ds_write_b16_d16_hi v14, v2 offset:19872
	v_sub_f32_e32 v2, v23, v0
	v_mul_f32_e32 v2, v1, v2
	v_mul_f32_e32 v2, v2, v4
	v_bfe_u32 v3, v2, 16, 1
	v_add3_u32 v2, v2, v3, s33
	ds_write_b16_d16_hi v14, v2 offset:20160
	v_sub_f32_e32 v2, v13, v0
	v_mul_f32_e32 v2, v1, v2
	v_mul_f32_e32 v2, v2, v5
	v_bfe_u32 v3, v2, 16, 1
	v_add3_u32 v2, v2, v3, s33
	ds_write_b16_d16_hi v14, v2 offset:20448
	v_lshlrev_b32_e32 v10, 16, v18
	v_sub_f32_e32 v10, v10, v0
	v_mul_f32_e32 v10, v1, v10
	v_and_b32_e32 v11, 0xffff0000, v18
	v_lshlrev_b32_e32 v12, 16, v19
	v_and_b32_e32 v13, 0xffff0000, v19
	v_lshlrev_b32_e32 v15, 16, v20
	v_and_b32_e32 v16, 0xffff0000, v20
	v_lshlrev_b32_e32 v18, 16, v21
	v_and_b32_e32 v19, 0xffff0000, v21
	s_waitcnt vmcnt(0)
	v_mov_b32_e32 v2, v88
	v_mov_b32_e32 v3, v89
	v_mov_b32_e32 v4, v90
	v_mov_b32_e32 v5, v91
	v_mov_b32_e32 v6, v92
	v_mov_b32_e32 v7, v93
	v_mov_b32_e32 v8, v94
	v_mov_b32_e32 v9, v95
	v_mul_f32_e32 v6, v10, v6
	v_bfe_u32 v10, v6, 16, 1
	v_add3_u32 v6, v6, v10, s33
	ds_write_b16_d16_hi v14, v6 offset:27648
	v_sub_f32_e32 v6, v11, v0
	v_mul_f32_e32 v6, v1, v6
	v_mul_f32_e32 v6, v6, v7
	v_bfe_u32 v7, v6, 16, 1
	v_add3_u32 v6, v6, v7, s33
	ds_write_b16_d16_hi v14, v6 offset:27936
	v_sub_f32_e32 v6, v12, v0
	v_mul_f32_e32 v6, v1, v6
	v_mul_f32_e32 v6, v6, v8
	v_bfe_u32 v7, v6, 16, 1
	v_add3_u32 v6, v6, v7, s33
	ds_write_b16_d16_hi v14, v6 offset:28224
	v_sub_f32_e32 v6, v13, v0
	v_mul_f32_e32 v6, v1, v6
	v_mul_f32_e32 v6, v6, v9
	v_bfe_u32 v7, v6, 16, 1
	v_add3_u32 v6, v6, v7, s33
	ds_write_b16_d16_hi v14, v6 offset:28512
	v_sub_f32_e32 v6, v15, v0
	v_mul_f32_e32 v6, v1, v6
	v_mul_f32_e32 v2, v6, v2
	v_bfe_u32 v6, v2, 16, 1
	v_add3_u32 v2, v2, v6, s33
	ds_write_b16_d16_hi v14, v2 offset:28800
	v_sub_f32_e32 v2, v16, v0
	v_mul_f32_e32 v2, v1, v2
	v_mul_f32_e32 v2, v2, v3
	v_bfe_u32 v3, v2, 16, 1
	v_add3_u32 v2, v2, v3, s33
	ds_write_b16_d16_hi v14, v2 offset:29088
	v_sub_f32_e32 v2, v18, v0
	v_sub_f32_e32 v0, v19, v0
	v_mul_f32_e32 v0, v1, v0
	v_mul_f32_e32 v2, v1, v2
	v_mul_f32_e32 v0, v0, v5
	v_mul_f32_e32 v2, v2, v4
	v_bfe_u32 v1, v0, 16, 1
	v_bfe_u32 v3, v2, 16, 1
	v_add3_u32 v0, v0, v1, s33
	v_add3_u32 v2, v2, v3, s33
	ds_write_b16_d16_hi v14, v0 offset:29664
	v_or_b32_e32 v0, s0, v36
	ds_write_b16_d16_hi v14, v2 offset:29376
	v_mad_u64_u32 v[2:3], s[0:1], v0, s3, v[60:61]
	v_and_b32_e32 v1, -16, v66
	v_readlane_b32 s0, v251, 12
	v_add_u32_e32 v0, v63, v1
	v_readlane_b32 s1, v251, 13
	s_andn2_b64 vcc, exec, s[0:1]
	v_add_u32_e32 v37, v2, v1
	v_mad_u32_u24 v38, v36, s3, v0
	s_waitcnt lgkmcnt(0)
	s_barrier
	s_cbranch_vccnz .LBB0_2601
	ds_read_b128 v[0:3], v37
	ds_read_b128 v[4:7], v38
	ds_read_b128 v[8:11], v38 offset:4608
	s_waitcnt lgkmcnt(1)
	v_mfma_f32_16x16x32_bf16 v[32:35], v[0:3], v[4:7], 0
	s_waitcnt lgkmcnt(0)
	v_mfma_f32_16x16x32_bf16 v[28:31], v[0:3], v[8:11], 0
	ds_read_b128 v[4:7], v38 offset:9216
	ds_read_b128 v[8:11], v38 offset:13824
	s_waitcnt lgkmcnt(1)
	v_mfma_f32_16x16x32_bf16 v[24:27], v[0:3], v[4:7], 0
	s_waitcnt lgkmcnt(0)
	v_mfma_f32_16x16x32_bf16 v[20:23], v[0:3], v[8:11], 0
	ds_read_b128 v[4:7], v38 offset:18432
	ds_read_b128 v[8:11], v38 offset:23040
	s_waitcnt lgkmcnt(1)
	v_mfma_f32_16x16x32_bf16 v[12:15], v[0:3], v[4:7], 0
	ds_read_b128 v[4:7], v38 offset:27648
	ds_read_b128 v[40:43], v38 offset:32256
	s_waitcnt lgkmcnt(2)
	v_mfma_f32_16x16x32_bf16 v[8:11], v[0:3], v[8:11], 0
	s_waitcnt lgkmcnt(1)
	v_mfma_f32_16x16x32_bf16 v[4:7], v[0:3], v[4:7], 0
	s_waitcnt lgkmcnt(0)
	v_mfma_f32_16x16x32_bf16 v[0:3], v[0:3], v[40:43], 0
	s_branch .LBB0_2602
